# NSA tile-list build parallelized over wave 0 lanes (was a serial loop in one lane)
# speedup vs baseline: 1.0038x; 1.0038x over previous
.LBB0_723:
	s_or_b64 exec, exec, s[6:7]
	s_waitcnt lgkmcnt(0)
	s_barrier
	v_cmp_eq_u32_e32 vcc, 0, v101
	s_and_saveexec_b64 s[6:7], vcc
	s_cbranch_execz .LBB0_740
	s_mov_b64 exec, s[6:7]
	v_mbcnt_lo_u32_b32 v0, -1, 0
	v_mbcnt_hi_u32_b32 v0, -1, v0
	v_and_b32_e32 v2, 31, v0
	v_lshrrev_b32_e32 v3, 5, v0
	v_lshlrev_b32_e32 v4, 2, v3
	v_add_u32_e32 v4, 0x18800, v4
	ds_read_b32 v5, v4
	ds_read_b32 v6, v4 offset:8
	v_lshlrev_b32_e64 v7, v2, 1
	v_add_u32_e32 v8, -1, v7
	s_waitcnt lgkmcnt(0)
	s_nop 0
	v_readlane_b32 s8, v5, 0
	v_readlane_b32 s9, v5, 32
	v_readlane_b32 s10, v6, 0
	v_readlane_b32 s11, v6, 32
	s_nop 3
	s_bcnt1_i32_b32 s12, s8
	s_bcnt1_i32_b32 s13, s9
	s_bcnt1_i32_b32 s14, s10
	s_bcnt1_i32_b32 s15, s11
	s_add_i32 s16, s12, s13
	s_add_i32 s17, s16, s14
	s_add_i32 s18, s17, s15
	v_and_b32_e32 v9, v5, v8
	v_bcnt_u32_b32 v9, v9, 0
	v_mov_b32_e32 v10, s12
	v_mul_u32_u24_e32 v10, v10, v3
	v_add_u32_e32 v9, v9, v10
	v_and_b32_e32 v11, v5, v7
	v_cmp_ne_u32_e32 vcc, 0, v11
	v_lshlrev_b32_e32 v9, 2, v9
	v_add_u32_e32 v9, 0x18820, v9
	s_and_saveexec_b64 s[20:21], vcc
	ds_write_b32 v9, v0
	s_or_b64 exec, exec, s[20:21]
	v_and_b32_e32 v9, v6, v8
	v_bcnt_u32_b32 v9, v9, 0
	v_mov_b32_e32 v10, s14
	v_mul_u32_u24_e32 v10, v10, v3
	v_add_u32_e32 v9, v9, v10
	v_add_u32_e32 v9, s16, v9
	v_and_b32_e32 v11, v6, v7
	v_cmp_ne_u32_e32 vcc, 0, v11
	v_add_u32_e32 v12, 64, v0
	v_lshlrev_b32_e32 v9, 2, v9
	v_add_u32_e32 v9, 0x18820, v9
	s_and_saveexec_b64 s[20:21], vcc
	ds_write_b32 v9, v12
	s_or_b64 exec, exec, s[20:21]
	v_readlane_b32 s9, v248, 12
	v_mov_b32_e32 v2, s18
	s_nop 1
	v_mov_b32_e32 v0, s9
	ds_write_b32 v0, v2
